# static priority raise for waves 4-7 in the attention phase removed (pipelined loops)
# baseline (speedup 1.0000x reference)
; #define ALAS __attribute__((address_space(3)))
; __device__ __forceinline__ void attn_phase(ALAS unsigned char* lds, const bf16_t* QK, const bf16_t* VT, bf16_t* Y, const float* rel_bias, const float* sinkp, const float* subln, const float* blam) {
;     ...
;       if (threadIdx.x < 128) ((ALAS float*)(lds + OFF_SUB))[threadIdx.x] = subln[threadIdx.x];
;       __syncthreads(); }
;     const int G = gridDim.x, bx = blockIdx.x;
;     if (__builtin_amdgcn_readfirstlane((int)threadIdx.x) >= 256) __builtin_amdgcn_s_setprio(1);
.LBB0_188:
	s_or_b64 exec, exec, s[0:1]
	v_readfirstlane_b32 s0, v230
	s_cmpk_lt_i32 s0, 0x100
	s_waitcnt lgkmcnt(0)
	s_barrier
	s_cbranch_scc1 .LBB0_190
	s_setprio 0
